# P0 silu loop unrolled (10 loads in flight) + modulation filler split across layer0/layer2 QKV idle slots
# speedup vs baseline: 1.0113x; 1.0113x over previous
.LBB0_9:
	s_or_b64 exec, exec, s[2:3]
	s_mov_b64 s[20:21], s[0:1]
	v_mov_b32_e32 v6, v214
	s_cmpk_gt_i32 s8, 0xbf
	s_cbranch_scc1 .LBB0_43
	s_movk_i32 s2, 0x13ff
	v_cmp_lt_i32_e32 vcc, s2, v6
	v_lshlrev_b32_e32 v1, 2, v6
	s_and_saveexec_b64 s[2:3], vcc
	s_xor_b64 s[2:3], exec, s[2:3]
	v_lshlrev_b32_e32 v1, 2, v6
	s_or_saveexec_b64 s[6:7], s[2:3]
	s_load_dwordx2 s[2:3], s[20:21], 0x88
	s_load_dwordx8 s[12:19], s[20:21], 0x28
	s_xor_b64 exec, exec, s[6:7]
	s_cbranch_execz .LBB0_20
	s_load_dwordx2 s[20:21], s[20:21], 0x10
	v_add_u32_e32 v7, 0, v1
	s_waitcnt lgkmcnt(0)
	global_load_dword v2, v1, s[12:13]
	global_load_dword v3, v1, s[12:13] offset:2048
	global_load_dword v4, v1, s[20:21]
	global_load_dword v5, v1, s[20:21] offset:2048
	s_add_u32 s22, s20, 0x1000
	s_addc_u32 s23, s21, 0
	global_load_dword v8, v1, s[22:23]
	global_load_dword v9, v1, s[22:23] offset:2048
	s_add_u32 s24, s20, 0x2000
	s_addc_u32 s25, s21, 0
	global_load_dword v10, v1, s[24:25]
	global_load_dword v11, v1, s[24:25] offset:2048
	s_add_u32 s26, s20, 0x3000
	s_addc_u32 s27, s21, 0
	global_load_dword v12, v1, s[26:27]
	global_load_dword v13, v1, s[26:27] offset:2048
	s_waitcnt vmcnt(9)
	v_mul_f32_e32 v16, 0xbfb8aa3b, v2
	v_exp_f32_e32 v16, v16
	s_nop 0
	v_add_f32_e32 v16, 1.0, v16
	v_div_scale_f32 v17, vcc, v16, v16, v2
	v_rcp_f32_e32 v18, v17
	v_div_scale_f32 v19, vcc, v2, v16, v2
	v_fma_f32 v20, -v17, v18, 1.0
	v_fmac_f32_e32 v18, v20, v18
	v_mul_f32_e32 v20, v19, v18
	v_fma_f32 v21, -v17, v20, v19
	v_fmac_f32_e32 v20, v21, v18
	v_fma_f32 v17, -v17, v20, v19
	v_div_fmas_f32 v17, v17, v18, v20
	v_div_fixup_f32 v2, v17, v16, v2
	ds_write_b32 v7, v2
	s_waitcnt vmcnt(8)
	v_mul_f32_e32 v16, 0xbfb8aa3b, v3
	v_exp_f32_e32 v16, v16
	s_nop 0
	v_add_f32_e32 v16, 1.0, v16
	v_div_scale_f32 v17, vcc, v16, v16, v3
	v_rcp_f32_e32 v18, v17
	v_div_scale_f32 v19, vcc, v3, v16, v3
	v_fma_f32 v20, -v17, v18, 1.0
	v_fmac_f32_e32 v18, v20, v18
	v_mul_f32_e32 v20, v19, v18
	v_fma_f32 v21, -v17, v20, v19
	v_fmac_f32_e32 v20, v21, v18
	v_fma_f32 v17, -v17, v20, v19
	v_div_fmas_f32 v17, v17, v18, v20
	v_div_fixup_f32 v3, v17, v16, v3
	ds_write_b32 v7, v3 offset:2048
	s_waitcnt vmcnt(7)
	v_mul_f32_e32 v16, 0xbfb8aa3b, v4
	v_exp_f32_e32 v16, v16
	s_nop 0
	v_add_f32_e32 v16, 1.0, v16
	v_div_scale_f32 v17, vcc, v16, v16, v4
	v_rcp_f32_e32 v18, v17
	v_div_scale_f32 v19, vcc, v4, v16, v4
	v_fma_f32 v20, -v17, v18, 1.0
	v_fmac_f32_e32 v18, v20, v18
	v_mul_f32_e32 v20, v19, v18
	v_fma_f32 v21, -v17, v20, v19
	v_fmac_f32_e32 v20, v21, v18
	v_fma_f32 v17, -v17, v20, v19
	v_div_fmas_f32 v17, v17, v18, v20
	v_div_fixup_f32 v4, v17, v16, v4
	ds_write_b32 v7, v4 offset:4096
	s_waitcnt vmcnt(6)
	v_mul_f32_e32 v16, 0xbfb8aa3b, v5
	v_exp_f32_e32 v16, v16
	s_nop 0
	v_add_f32_e32 v16, 1.0, v16
	v_div_scale_f32 v17, vcc, v16, v16, v5
	v_rcp_f32_e32 v18, v17
	v_div_scale_f32 v19, vcc, v5, v16, v5
	v_fma_f32 v20, -v17, v18, 1.0
	v_fmac_f32_e32 v18, v20, v18
	v_mul_f32_e32 v20, v19, v18
	v_fma_f32 v21, -v17, v20, v19
	v_fmac_f32_e32 v20, v21, v18
	v_fma_f32 v17, -v17, v20, v19
	v_div_fmas_f32 v17, v17, v18, v20
	v_div_fixup_f32 v5, v17, v16, v5
	ds_write_b32 v7, v5 offset:6144
	s_waitcnt vmcnt(5)
	v_mul_f32_e32 v16, 0xbfb8aa3b, v8
	v_exp_f32_e32 v16, v16
	s_nop 0
	v_add_f32_e32 v16, 1.0, v16
	v_div_scale_f32 v17, vcc, v16, v16, v8
	v_rcp_f32_e32 v18, v17
	v_div_scale_f32 v19, vcc, v8, v16, v8
	v_fma_f32 v20, -v17, v18, 1.0
	v_fmac_f32_e32 v18, v20, v18
	v_mul_f32_e32 v20, v19, v18
	v_fma_f32 v21, -v17, v20, v19
	v_fmac_f32_e32 v20, v21, v18
	v_fma_f32 v17, -v17, v20, v19
	v_div_fmas_f32 v17, v17, v18, v20
	v_div_fixup_f32 v8, v17, v16, v8
	ds_write_b32 v7, v8 offset:8192
	s_waitcnt vmcnt(4)
	v_mul_f32_e32 v16, 0xbfb8aa3b, v9
	v_exp_f32_e32 v16, v16
	s_nop 0
	v_add_f32_e32 v16, 1.0, v16
	v_div_scale_f32 v17, vcc, v16, v16, v9
	v_rcp_f32_e32 v18, v17
	v_div_scale_f32 v19, vcc, v9, v16, v9
	v_fma_f32 v20, -v17, v18, 1.0
	v_fmac_f32_e32 v18, v20, v18
	v_mul_f32_e32 v20, v19, v18
	v_fma_f32 v21, -v17, v20, v19
	v_fmac_f32_e32 v20, v21, v18
	v_fma_f32 v17, -v17, v20, v19
	v_div_fmas_f32 v17, v17, v18, v20
	v_div_fixup_f32 v9, v17, v16, v9
	ds_write_b32 v7, v9 offset:10240
	s_waitcnt vmcnt(3)
	v_mul_f32_e32 v16, 0xbfb8aa3b, v10
	v_exp_f32_e32 v16, v16
	s_nop 0
	v_add_f32_e32 v16, 1.0, v16
	v_div_scale_f32 v17, vcc, v16, v16, v10
	v_rcp_f32_e32 v18, v17
	v_div_scale_f32 v19, vcc, v10, v16, v10
	v_fma_f32 v20, -v17, v18, 1.0
	v_fmac_f32_e32 v18, v20, v18
	v_mul_f32_e32 v20, v19, v18
	v_fma_f32 v21, -v17, v20, v19
	v_fmac_f32_e32 v20, v21, v18
	v_fma_f32 v17, -v17, v20, v19
	v_div_fmas_f32 v17, v17, v18, v20
	v_div_fixup_f32 v10, v17, v16, v10
	ds_write_b32 v7, v10 offset:12288
	s_waitcnt vmcnt(2)
	v_mul_f32_e32 v16, 0xbfb8aa3b, v11
	v_exp_f32_e32 v16, v16
	s_nop 0
	v_add_f32_e32 v16, 1.0, v16
	v_div_scale_f32 v17, vcc, v16, v16, v11
	v_rcp_f32_e32 v18, v17
	v_div_scale_f32 v19, vcc, v11, v16, v11
	v_fma_f32 v20, -v17, v18, 1.0
	v_fmac_f32_e32 v18, v20, v18
	v_mul_f32_e32 v20, v19, v18
	v_fma_f32 v21, -v17, v20, v19
	v_fmac_f32_e32 v20, v21, v18
	v_fma_f32 v17, -v17, v20, v19
	v_div_fmas_f32 v17, v17, v18, v20
	v_div_fixup_f32 v11, v17, v16, v11
	ds_write_b32 v7, v11 offset:14336
	s_waitcnt vmcnt(1)
	v_mul_f32_e32 v16, 0xbfb8aa3b, v12
	v_exp_f32_e32 v16, v16
	s_nop 0
	v_add_f32_e32 v16, 1.0, v16
	v_div_scale_f32 v17, vcc, v16, v16, v12
	v_rcp_f32_e32 v18, v17
	v_div_scale_f32 v19, vcc, v12, v16, v12
	v_fma_f32 v20, -v17, v18, 1.0
	v_fmac_f32_e32 v18, v20, v18
	v_mul_f32_e32 v20, v19, v18
	v_fma_f32 v21, -v17, v20, v19
	v_fmac_f32_e32 v20, v21, v18
	v_fma_f32 v17, -v17, v20, v19
	v_div_fmas_f32 v17, v17, v18, v20
	v_div_fixup_f32 v12, v17, v16, v12
	ds_write_b32 v7, v12 offset:16384
	s_waitcnt vmcnt(0)
	v_mul_f32_e32 v16, 0xbfb8aa3b, v13
	v_exp_f32_e32 v16, v16
	s_nop 0
	v_add_f32_e32 v16, 1.0, v16
	v_div_scale_f32 v17, vcc, v16, v16, v13
	v_rcp_f32_e32 v18, v17
	v_div_scale_f32 v19, vcc, v13, v16, v13
	v_fma_f32 v20, -v17, v18, 1.0
	v_fmac_f32_e32 v18, v20, v18
	v_mul_f32_e32 v20, v19, v18
	v_fma_f32 v21, -v17, v20, v19
	v_fmac_f32_e32 v20, v21, v18
	v_fma_f32 v17, -v17, v20, v19
	v_div_fmas_f32 v17, v17, v18, v20
	v_div_fixup_f32 v13, v17, v16, v13
	ds_write_b32 v7, v13 offset:18432

.LBB0_301:
	s_movk_i32 s100, 0x240
	s_movk_i32 s101, 0x300
	s_cmp_eq_u32 s36, 0
	s_cselect_b32 s101, s100, s101
	s_cselect_b32 s100, 0xc0, s100
	s_branch .LBB0_377

.LBB0_376:
	s_waitcnt vmcnt(0)
	v_readlane_b32 s96, v255, 13
	s_movk_i32 s97, 0x800
	s_movk_i32 s90, 0xff00
	s_movk_i32 s91, 0x2000
	s_barrier
	s_movk_i32 s100, 0x240
	s_movk_i32 s101, 0x300
	s_cmp_eq_u32 s36, 0
	s_cselect_b32 s101, s100, s101
	s_cselect_b32 s100, 0xc0, s100

.LBB0_389:
	s_cmp_lt_i32 s26, 0
	s_cbranch_scc1 .LBB0_429
	s_mov_b64 s[6:7], s[0:1]
	v_mov_b32_e32 v2, v214
	s_sub_i32 s2, s101, s100
	s_cmp_ge_u32 s26, s2
	s_cbranch_scc1 .LBB0_429
	s_movk_i32 s2, 0x13ff
	v_cmp_lt_i32_e32 vcc, s2, v2
	v_lshlrev_b32_e32 v3, 2, v2
	s_and_saveexec_b64 s[2:3], vcc
	s_xor_b64 s[2:3], exec, s[2:3]
	v_lshlrev_b32_e32 v3, 2, v2
	s_or_saveexec_b64 s[4:5], s[2:3]
	s_load_dwordx8 s[16:23], s[6:7], 0x28
	s_load_dwordx2 s[2:3], s[6:7], 0x88
	s_xor_b64 exec, exec, s[4:5]
	s_cbranch_execz .LBB0_406
	s_load_dwordx2 s[6:7], s[6:7], 0x10
	v_add_u32_e32 v4, 0, v3
	s_mov_b64 s[14:15], 0
	v_mov_b32_e32 v5, v2
	s_branch .LBB0_396

.LBB0_406:
	s_or_b64 exec, exec, s[4:5]
	s_add_i32 s26, s26, s100
	v_and_b32_e32 v60, 31, v2
	s_waitcnt lgkmcnt(0)
	s_add_u32 s4, s2, 0x4e00000
	v_ashrrev_i32_e32 v56, 3, v2
	v_and_b32_e32 v0, 28, v3
	s_movk_i32 s2, 0xa0
	v_ashrrev_i32_e32 v58, 5, v2
	s_movk_i32 s6, 0x280
	v_lshlrev_b32_e32 v3, 2, v60
	s_addc_u32 s5, s3, 0
	v_lshl_add_u32 v1, v0, 2, 0
	v_cmp_gt_i32_e64 s[2:3], s2, v2
	v_mul_lo_u32 v2, v56, s6
	v_lshl_or_b32 v3, v58, 7, v3
	v_ashrrev_i32_e32 v57, 31, v56
	v_lshl_add_u32 v59, v56, 2, 0
	v_add_u32_e32 v61, 0, v3
	v_lshlrev_b32_e32 v96, 2, v0
	v_add_u32_e32 v74, v1, v2
	s_waitcnt vmcnt(0)
	s_barrier
	s_branch .LBB0_410

.LBB0_409:
	s_or_b64 exec, exec, s[16:17]
	s_add_i32 s26, s26, s96
	s_cmp_lt_i32 s26, s101
	s_barrier
	s_cbranch_scc0 .LBB0_429

	.amdhsa_kernel _Z8mega_fwd6Params
		.amdhsa_group_segment_fixed_size 0
		.amdhsa_private_segment_fixed_size 0
		.amdhsa_kernarg_size 400
		.amdhsa_user_sgpr_count 2
		.amdhsa_user_sgpr_dispatch_ptr 0
		.amdhsa_user_sgpr_queue_ptr 0
		.amdhsa_user_sgpr_kernarg_segment_ptr 1
		.amdhsa_user_sgpr_dispatch_id 0
		.amdhsa_user_sgpr_kernarg_preload_length 0
		.amdhsa_user_sgpr_kernarg_preload_offset 0
		.amdhsa_user_sgpr_private_segment_size 0
		.amdhsa_uses_dynamic_stack 0
		.amdhsa_enable_private_segment 0
		.amdhsa_system_sgpr_workgroup_id_x 1
		.amdhsa_system_sgpr_workgroup_id_y 0
		.amdhsa_system_sgpr_workgroup_id_z 0
		.amdhsa_system_sgpr_workgroup_info 0
		.amdhsa_system_vgpr_workitem_id 2
		.amdhsa_next_free_vgpr 256
		.amdhsa_next_free_sgpr 102
		.amdhsa_accum_offset 256
		.amdhsa_reserve_vcc 1
		.amdhsa_float_round_mode_32 0
		.amdhsa_float_round_mode_16_64 0
		.amdhsa_float_denorm_mode_32 3
		.amdhsa_float_denorm_mode_16_64 3
		.amdhsa_dx10_clamp 1
		.amdhsa_ieee_mode 1
		.amdhsa_fp16_overflow 0
		.amdhsa_tg_split 0
		.amdhsa_exception_fp_ieee_invalid_op 0
		.amdhsa_exception_fp_denorm_src 0
		.amdhsa_exception_fp_ieee_div_zero 0
		.amdhsa_exception_fp_ieee_overflow 0
		.amdhsa_exception_fp_ieee_underflow 0
		.amdhsa_exception_fp_ieee_inexact 0
		.amdhsa_exception_int_div_zero 0
	.end_amdhsa_kernel

amdhsa.kernels:
  - .agpr_count:     0
    .args:
      - .offset:         0
        .size:           144
        .value_kind:     by_value
      - .offset:         144
        .size:           4
        .value_kind:     hidden_block_count_x
      - .offset:         148
        .size:           4
        .value_kind:     hidden_block_count_y
      - .offset:         152
        .size:           4
        .value_kind:     hidden_block_count_z
      - .offset:         156
        .size:           2
        .value_kind:     hidden_group_size_x
      - .offset:         158
        .size:           2
        .value_kind:     hidden_group_size_y
      - .offset:         160
        .size:           2
        .value_kind:     hidden_group_size_z
      - .offset:         162
        .size:           2
        .value_kind:     hidden_remainder_x
      - .offset:         164
        .size:           2
        .value_kind:     hidden_remainder_y
      - .offset:         166
        .size:           2
        .value_kind:     hidden_remainder_z
      - .offset:         184
        .size:           8
        .value_kind:     hidden_global_offset_x
      - .offset:         192
        .size:           8
        .value_kind:     hidden_global_offset_y
      - .offset:         200
        .size:           8
        .value_kind:     hidden_global_offset_z
      - .offset:         208
        .size:           2
        .value_kind:     hidden_grid_dims
      - .offset:         232
        .size:           8
        .value_kind:     hidden_multigrid_sync_arg
      - .offset:         264
        .size:           4
        .value_kind:     hidden_dynamic_lds_size
    .group_segment_fixed_size: 0
    .kernarg_segment_align: 8
    .kernarg_segment_size: 400
    .language:       OpenCL C
    .language_version:
      - 2
      - 0
    .max_flat_workgroup_size: 512
    .name:           _Z8mega_fwd6Params
    .private_segment_fixed_size: 0
    .sgpr_count:     108
    .sgpr_spill_count: 16
    .symbol:         _Z8mega_fwd6Params.kd
    .uniform_work_group_size: 1
    .uses_dynamic_stack: false
    .vgpr_count:     256
    .vgpr_spill_count: 0
    .wavefront_size: 64
